# adds: diff k_post 4 pass loads issued up front; fused resid+norm epilogue prefetches all 16 fp16 residual tiles with counted waits; MLA post pass hoists per-row gain loads out of the row loop and batc
# speedup vs baseline: 1.0259x; 1.0137x over previous
.LBB0_204:
	s_waitcnt lgkmcnt(0)
	v_cmp_lt_i32_e64 s[8:9], s31, v6
	v_mov_b32_e32 v2, v6
	s_and_saveexec_b64 s[16:17], s[8:9]
	v_add_u32_e32 v2, 0xffffe000, v6
	v_lshrrev_b32_e32 v2, 12, v2
	v_mul_u32_u24_e32 v2, 0x1200, v2
	v_and_b32_e32 v3, 0xfff, v6
	v_add3_u32 v2, v2, v3, s86
	s_or_b64 exec, exec, s[16:17]
	v_ashrrev_i32_e32 v3, 31, v2
	v_lshlrev_b64 v[2:3], 11, v[2:3]
	v_lshl_add_u64 v[12:13], v[8:9], 0, v[2:3]
	global_load_dwordx2 v[2:3], v[12:13], off
	global_load_dwordx2 v[30:31], v[12:13], off offset:512
	global_load_dwordx2 v[32:33], v[12:13], off offset:1024
	global_load_dwordx2 v[34:35], v[12:13], off offset:1536
	v_lshrrev_b32_e32 v4, 6, v6
	v_cndmask_b32_e64 v4, v6, v4, s[6:7]
	v_and_b32_e32 v4, 63, v4
	v_cvt_f32_ubyte0_e32 v4, v4
	v_mul_f32_e32 v5, v24, v4
	v_mul_f32_e32 v7, v25, v4
	v_mul_f32_e32 v14, v26, v4
	v_mul_f32_e32 v4, v27, v4
	v_mul_f32_e32 v5, 0.15915494, v5
	v_mul_f32_e32 v7, 0.15915494, v7
	v_mul_f32_e32 v15, 0.15915494, v14
	v_mul_f32_e32 v4, 0.15915494, v4
	v_cos_f32_e32 v18, v5
	v_sin_f32_e32 v20, v5
	v_cos_f32_e32 v14, v7
	v_sin_f32_e32 v16, v7
	v_cos_f32_e32 v19, v15
	v_sin_f32_e32 v21, v15
	v_cos_f32_e32 v15, v4
	v_sin_f32_e32 v17, v4
	s_waitcnt vmcnt(3)
	v_and_b32_e32 v4, 0xffff0000, v2
	v_lshlrev_b32_e32 v22, 16, v2
	v_and_b32_e32 v5, 0xffff0000, v3
	v_lshlrev_b32_e32 v23, 16, v3
	s_and_saveexec_b64 s[16:17], s[8:9]
	s_xor_b64 s[16:17], exec, s[16:17]
	s_cbranch_execz .LBB0_208
	ds_bpermute_b32 v2, v0, v22
	ds_bpermute_b32 v3, v0, v23
	ds_bpermute_b32 v28, v0, v4
	ds_bpermute_b32 v29, v0, v5
	s_waitcnt lgkmcnt(2)
	v_pk_mul_f32 v[2:3], v[20:21], v[2:3]
	s_nop 0
	v_cndmask_b32_e64 v3, v3, -v3, vcc
	v_cndmask_b32_e64 v2, v2, -v2, vcc
	v_pk_fma_f32 v[2:3], v[18:19], v[22:23], v[2:3]
	s_waitcnt lgkmcnt(0)
	v_pk_mul_f32 v[22:23], v[16:17], v[28:29]
	v_and_b32_sdwa v7, v3, v196 dst_sel:DWORD dst_unused:UNUSED_PAD src0_sel:WORD_1 src1_sel:DWORD
	v_cndmask_b32_e64 v23, v23, -v23, vcc
	v_cndmask_b32_e64 v22, v22, -v22, vcc
	v_pk_fma_f32 v[4:5], v[14:15], v[4:5], v[22:23]
	v_and_b32_sdwa v22, v2, v196 dst_sel:DWORD dst_unused:UNUSED_PAD src0_sel:WORD_1 src1_sel:DWORD
	v_add3_u32 v2, v2, v22, s44
	v_add3_u32 v3, v3, v7, s44
	v_and_b32_sdwa v7, v5, v196 dst_sel:DWORD dst_unused:UNUSED_PAD src0_sel:WORD_1 src1_sel:DWORD
	v_and_b32_sdwa v22, v4, v196 dst_sel:DWORD dst_unused:UNUSED_PAD src0_sel:WORD_1 src1_sel:DWORD
	v_add3_u32 v5, v5, v7, s44
	v_add3_u32 v4, v4, v22, s44
	v_and_b32_e32 v5, 0xffff0000, v5
	v_and_b32_e32 v4, 0xffff0000, v4
	v_or_b32_sdwa v3, v5, v3 dst_sel:DWORD dst_unused:UNUSED_PAD src0_sel:DWORD src1_sel:WORD_1
	v_or_b32_sdwa v2, v4, v2 dst_sel:DWORD dst_unused:UNUSED_PAD src0_sel:DWORD src1_sel:WORD_1
	global_store_dwordx2 v[12:13], v[2:3], off

.LBB0_210:
	s_or_b64 exec, exec, s[16:17]
	s_waitcnt vmcnt(3)
	v_and_b32_e32 v4, 0xffff0000, v30
	v_lshlrev_b32_e32 v22, 16, v30
	v_and_b32_e32 v5, 0xffff0000, v31
	v_lshlrev_b32_e32 v23, 16, v31
	s_and_saveexec_b64 s[16:17], s[8:9]
	s_xor_b64 s[16:17], exec, s[16:17]
	s_cbranch_execz .LBB0_212
	ds_bpermute_b32 v2, v0, v22
	ds_bpermute_b32 v3, v0, v23
	ds_bpermute_b32 v28, v0, v4
	ds_bpermute_b32 v29, v0, v5
	s_waitcnt lgkmcnt(2)
	v_pk_mul_f32 v[2:3], v[20:21], v[2:3]
	s_nop 0
	v_cndmask_b32_e64 v3, v3, -v3, vcc
	v_cndmask_b32_e64 v2, v2, -v2, vcc
	v_pk_fma_f32 v[2:3], v[18:19], v[22:23], v[2:3]
	s_waitcnt lgkmcnt(0)
	v_pk_mul_f32 v[22:23], v[16:17], v[28:29]
	v_and_b32_sdwa v7, v3, v196 dst_sel:DWORD dst_unused:UNUSED_PAD src0_sel:WORD_1 src1_sel:DWORD
	v_cndmask_b32_e64 v23, v23, -v23, vcc
	v_cndmask_b32_e64 v22, v22, -v22, vcc
	v_pk_fma_f32 v[4:5], v[14:15], v[4:5], v[22:23]
	v_and_b32_sdwa v22, v2, v196 dst_sel:DWORD dst_unused:UNUSED_PAD src0_sel:WORD_1 src1_sel:DWORD
	v_add3_u32 v2, v2, v22, s44
	v_add3_u32 v3, v3, v7, s44
	v_and_b32_sdwa v7, v5, v196 dst_sel:DWORD dst_unused:UNUSED_PAD src0_sel:WORD_1 src1_sel:DWORD
	v_and_b32_sdwa v22, v4, v196 dst_sel:DWORD dst_unused:UNUSED_PAD src0_sel:WORD_1 src1_sel:DWORD
	v_add3_u32 v5, v5, v7, s44
	v_add3_u32 v4, v4, v22, s44
	v_and_b32_e32 v5, 0xffff0000, v5
	v_and_b32_e32 v4, 0xffff0000, v4
	v_or_b32_sdwa v3, v5, v3 dst_sel:DWORD dst_unused:UNUSED_PAD src0_sel:DWORD src1_sel:WORD_1
	v_or_b32_sdwa v2, v4, v2 dst_sel:DWORD dst_unused:UNUSED_PAD src0_sel:DWORD src1_sel:WORD_1
	global_store_dwordx2 v[12:13], v[2:3], off offset:512

.LBB0_214:
	s_or_b64 exec, exec, s[16:17]
	s_waitcnt vmcnt(3)
	v_and_b32_e32 v4, 0xffff0000, v32
	v_lshlrev_b32_e32 v22, 16, v32
	v_and_b32_e32 v5, 0xffff0000, v33
	v_lshlrev_b32_e32 v23, 16, v33
	s_and_saveexec_b64 s[16:17], s[8:9]
	s_xor_b64 s[16:17], exec, s[16:17]
	s_cbranch_execz .LBB0_216
	ds_bpermute_b32 v2, v0, v22
	ds_bpermute_b32 v3, v0, v23
	ds_bpermute_b32 v28, v0, v4
	ds_bpermute_b32 v29, v0, v5
	s_waitcnt lgkmcnt(2)
	v_pk_mul_f32 v[2:3], v[20:21], v[2:3]
	s_nop 0
	v_cndmask_b32_e64 v3, v3, -v3, vcc
	v_cndmask_b32_e64 v2, v2, -v2, vcc
	v_pk_fma_f32 v[2:3], v[18:19], v[22:23], v[2:3]
	s_waitcnt lgkmcnt(0)
	v_pk_mul_f32 v[22:23], v[16:17], v[28:29]
	v_and_b32_sdwa v7, v3, v196 dst_sel:DWORD dst_unused:UNUSED_PAD src0_sel:WORD_1 src1_sel:DWORD
	v_cndmask_b32_e64 v23, v23, -v23, vcc
	v_cndmask_b32_e64 v22, v22, -v22, vcc
	v_pk_fma_f32 v[4:5], v[14:15], v[4:5], v[22:23]
	v_and_b32_sdwa v22, v2, v196 dst_sel:DWORD dst_unused:UNUSED_PAD src0_sel:WORD_1 src1_sel:DWORD
	v_add3_u32 v2, v2, v22, s44
	v_add3_u32 v3, v3, v7, s44
	v_and_b32_sdwa v7, v5, v196 dst_sel:DWORD dst_unused:UNUSED_PAD src0_sel:WORD_1 src1_sel:DWORD
	v_and_b32_sdwa v22, v4, v196 dst_sel:DWORD dst_unused:UNUSED_PAD src0_sel:WORD_1 src1_sel:DWORD
	v_add3_u32 v5, v5, v7, s44
	v_add3_u32 v4, v4, v22, s44
	v_and_b32_e32 v5, 0xffff0000, v5
	v_and_b32_e32 v4, 0xffff0000, v4
	v_or_b32_sdwa v3, v5, v3 dst_sel:DWORD dst_unused:UNUSED_PAD src0_sel:DWORD src1_sel:WORD_1
	v_or_b32_sdwa v2, v4, v2 dst_sel:DWORD dst_unused:UNUSED_PAD src0_sel:DWORD src1_sel:WORD_1
	global_store_dwordx2 v[12:13], v[2:3], off offset:1024

.LBB0_218:
	s_or_b64 exec, exec, s[16:17]
	s_waitcnt vmcnt(3)
	v_and_b32_e32 v4, 0xffff0000, v34
	v_lshlrev_b32_e32 v22, 16, v34
	v_and_b32_e32 v5, 0xffff0000, v35
	v_lshlrev_b32_e32 v23, 16, v35
	s_and_saveexec_b64 s[16:17], s[8:9]
	s_xor_b64 s[8:9], exec, s[16:17]
	s_cbranch_execz .LBB0_220
	ds_bpermute_b32 v2, v0, v22
	ds_bpermute_b32 v3, v0, v23
	ds_bpermute_b32 v28, v0, v4
	ds_bpermute_b32 v29, v0, v5
	s_waitcnt lgkmcnt(2)
	v_pk_mul_f32 v[2:3], v[20:21], v[2:3]
	s_nop 0
	v_cndmask_b32_e64 v3, v3, -v3, vcc
	v_cndmask_b32_e64 v2, v2, -v2, vcc
	s_waitcnt lgkmcnt(0)
	v_pk_mul_f32 v[16:17], v[16:17], v[28:29]
	v_pk_fma_f32 v[2:3], v[18:19], v[22:23], v[2:3]
	v_cndmask_b32_e64 v17, v17, -v17, vcc
	v_cndmask_b32_e64 v16, v16, -v16, vcc
	v_pk_fma_f32 v[4:5], v[14:15], v[4:5], v[16:17]
	v_and_b32_sdwa v7, v3, v196 dst_sel:DWORD dst_unused:UNUSED_PAD src0_sel:WORD_1 src1_sel:DWORD
	v_and_b32_sdwa v14, v2, v196 dst_sel:DWORD dst_unused:UNUSED_PAD src0_sel:WORD_1 src1_sel:DWORD
	v_add3_u32 v2, v2, v14, s44
	v_add3_u32 v3, v3, v7, s44
	v_and_b32_sdwa v7, v5, v196 dst_sel:DWORD dst_unused:UNUSED_PAD src0_sel:WORD_1 src1_sel:DWORD
	v_and_b32_sdwa v14, v4, v196 dst_sel:DWORD dst_unused:UNUSED_PAD src0_sel:WORD_1 src1_sel:DWORD
	v_add3_u32 v5, v5, v7, s44
	v_add3_u32 v4, v4, v14, s44
	v_and_b32_e32 v5, 0xffff0000, v5
	v_and_b32_e32 v4, 0xffff0000, v4
	v_or_b32_sdwa v3, v5, v3 dst_sel:DWORD dst_unused:UNUSED_PAD src0_sel:DWORD src1_sel:WORD_1
	v_or_b32_sdwa v2, v4, v2 dst_sel:DWORD dst_unused:UNUSED_PAD src0_sel:DWORD src1_sel:WORD_1
	global_store_dwordx2 v[12:13], v[2:3], off offset:1536

.LBB0_252:
	s_andn2_b64 vcc, exec, s[0:1]
	s_cbranch_vccnz .LBB0_393
	s_and_b64 s[0:1], s[12:13], exec
	s_cselect_b32 s0, 0x880000, 0
	v_readlane_b32 s2, v255, 5
	v_readlane_b32 s3, v255, 6
	s_add_u32 s0, s2, s0
	s_addc_u32 s1, s3, 0
	v_writelane_b32 v255, s0, 16
	s_nop 1
	v_writelane_b32 v255, s1, 17
	s_nop 0
	v_readlane_b32 s0, v255, 14
	s_cmp_gt_i32 s0, 4
	s_mov_b64 s[0:1], -1
	s_cbranch_scc0 .LBB0_276
	v_mov_b32_e32 v8, v197
	s_mov_b32 s17, s66
	v_mov_b32_e32 v0, v197
	v_readlane_b32 s0, v254, 56
	v_ashrrev_i32_e32 v3, 6, v0
	v_lshl_add_u32 v2, s17, 3, v3
	s_mov_b32 s18, s0
	s_movk_i32 s0, 0x4000
	v_readlane_b32 s1, v254, 57
	v_cmp_gt_i32_e32 vcc, s0, v2
	s_and_saveexec_b64 s[0:1], vcc
	s_mov_b32 s40, 0x3b800000
	s_mov_b32 s41, 0x3b2aaaab
	s_movk_i32 s37, 0x1fff
	s_cbranch_execz .LBB0_275
	s_add_u32 s2, s24, 0x4000000
	s_waitcnt lgkmcnt(0)
	s_load_dwordx4 s[8:11], s[96:97], 0xa0
	s_addc_u32 s3, s25, 0
	s_add_u32 s4, s24, 0x5000000
	s_addc_u32 s5, s25, 0
	s_lshl_b32 s16, s18, 3
	s_and_b64 s[6:7], s[12:13], exec
	s_cselect_b32 s6, 0x400, 0
	s_waitcnt lgkmcnt(0)
	s_add_u32 s20, s10, s6
	s_addc_u32 s21, s11, 0
	s_and_b64 s[6:7], s[12:13], exec
	s_cselect_b32 s6, 0x600, 0
	v_cndmask_b32_e64 v5, 0, 1, s[12:13]
	s_add_u32 s12, s8, s6
	v_and_b32_e32 v4, 63, v8
	v_and_b32_e32 v9, 16, v8
	s_addc_u32 s13, s9, 0
	v_lshlrev_b32_e32 v12, 2, v4
	v_cmp_eq_u32_e64 s[8:9], 0, v9
	v_and_b32_e32 v9, 7, v8
	v_mov_b32_e32 v13, v1
	v_cvt_f32_ubyte0_e32 v9, v9
	v_lshl_add_u64 v[10:11], s[12:13], 0, v[12:13]
	v_lshlrev_b32_e32 v14, 5, v3
	s_movk_i32 s12, 0x300
	v_mul_f32_e32 v9, 0xbfd49a78, v9
	v_lshl_add_u32 v38, s17, 8, v14
	v_mad_i64_i32 v[14:15], s[12:13], v2, s12, 0
	v_exp_f32_e32 v37, v9
	s_movk_i32 s12, 0x600
	v_lshlrev_b32_e32 v0, 1, v4
	v_readlane_b32 s6, v255, 16
	v_and_b32_e32 v20, 31, v8
	v_mad_i64_i32 v[18:19], s[12:13], v2, s12, 0
	v_readlane_b32 s7, v255, 17
	v_and_b32_e32 v8, 8, v8
	v_lshlrev_b32_e32 v3, 8, v3
	v_or_b32_e32 v16, v18, v0
	v_lshl_or_b32 v18, v20, 1, v18
	s_mov_b64 s[12:13], 0xf8ac600
	v_xor_b32_e32 v32, 4, v12
	v_xor_b32_e32 v33, 8, v12
	v_xor_b32_e32 v34, 16, v12
	v_xor_b32_e32 v35, 32, v12
	v_xor_b32_e32 v36, 64, v12
	v_lshl_add_u64 v[6:7], s[6:7], 0, v[0:1]
	v_cmp_gt_u32_e64 s[6:7], 32, v4
	v_cmp_eq_u32_e64 s[10:11], 0, v8
	v_lshl_add_u64 v[8:9], s[14:15], 0, v[0:1]
	v_lshl_add_u64 v[12:13], s[20:21], 0, v[12:13]
	s_lshl_b32 s31, s18, 8
	v_lshl_add_u32 v39, s17, 11, v3
	s_lshl_b32 s36, s18, 11
	v_ashrrev_i32_e32 v3, 31, v2
	s_ashr_i32 s17, s16, 31
	v_or_b32_e32 v14, v14, v0
	s_mul_i32 s20, s18, 0x1800
	s_mul_hi_i32 s21, s16, 0x300
	v_mov_b32_e32 v17, v19
	s_mul_i32 s28, s18, 0x3000
	s_mul_hi_i32 s29, s16, 0x600
	v_lshl_add_u64 v[18:19], v[18:19], 0, s[12:13]
	global_load_dword v50, v[10:11], off
	global_load_dword v51, v[10:11], off offset:256
	global_load_dword v52, v[10:11], off offset:512
	global_load_dword v53, v[10:11], off offset:768
	global_load_dword v54, v[10:11], off offset:1024
	global_load_dword v55, v[10:11], off offset:1280
	global_load_dword v56, v[12:13], off
	global_load_dword v57, v[12:13], off offset:256
	global_load_dword v58, v[12:13], off offset:512
	global_load_dword v59, v[12:13], off offset:768
	s_mov_b64 s[34:35], 0
	s_waitcnt vmcnt(0)
	s_branch .LBB0_258

.LBB0_260:
	s_or_b64 exec, exec, s[18:19]
	v_lshl_add_u64 v[22:23], s[26:27], 0, v[16:17]
	v_add_co_u32_e32 v24, vcc, 0xf8ac000, v22
	s_nop 1
	v_addc_co_u32_e32 v25, vcc, 0, v23, vcc
	s_waitcnt lgkmcnt(0)
	global_load_ushort v0, v[24:25], off offset:256
	global_load_ushort v22, v[24:25], off offset:384
	global_load_ushort v61, v[24:25], off offset:512
	global_load_ushort v62, v[24:25], off offset:640
	global_load_ushort v63, v[24:25], off offset:768
	global_load_ushort v64, v[24:25], off offset:896
	v_lshl_add_u64 v[66:67], s[26:27], 0, v[18:19]
	global_load_ushort v60, v[66:67], off
	s_waitcnt vmcnt(5)
	v_lshlrev_b32_e32 v0, 16, v0
	v_lshlrev_b32_e32 v46, 16, v22
	v_mul_f32_e32 v47, v46, v46
	v_fmac_f32_e32 v47, v0, v0
	s_waitcnt vmcnt(3)
	v_lshlrev_b32_e32 v28, 16, v61
	v_lshlrev_b32_e32 v29, 16, v62
	v_pk_mul_f32 v[30:31], v[28:29], v[28:29]
	s_waitcnt vmcnt(1)
	v_lshlrev_b32_e32 v26, 16, v63
	v_lshlrev_b32_e32 v27, 16, v64
	global_load_ushort v22, v[24:25], off offset:1024
	global_load_ushort v23, v[24:25], off offset:1152
	global_load_ushort v44, v[24:25], off offset:1280
	s_nop 0
	global_load_ushort v24, v[24:25], off offset:1408
	v_add_f32_e32 v30, v47, v30
	v_pk_mul_f32 v[40:41], v[26:27], v[26:27]
	v_add_f32_e32 v30, v30, v31
	v_add_f32_e32 v30, v30, v40
	v_add_f32_e32 v30, v30, v41
	ds_bpermute_b32 v31, v32, v30
	s_waitcnt lgkmcnt(0)
	v_add_f32_e32 v30, v30, v31
	ds_bpermute_b32 v31, v33, v30
	s_waitcnt lgkmcnt(0)
	v_add_f32_e32 v30, v30, v31
	ds_bpermute_b32 v31, v34, v30
	s_waitcnt lgkmcnt(0)
	v_add_f32_e32 v30, v30, v31
	ds_bpermute_b32 v31, v35, v30
	s_waitcnt lgkmcnt(0)
	v_add_f32_e32 v30, v30, v31
	ds_bpermute_b32 v31, v36, v30
	s_waitcnt lgkmcnt(0)
	v_add_f32_e32 v31, v30, v31
	v_mov_b32_e32 v41, v31
	v_nop
	v_nop
	v_permlane32_swap_b32 v31, v41
	s_waitcnt vmcnt(3)
	v_lshlrev_b32_e32 v22, 16, v22
	s_waitcnt vmcnt(2)
	v_lshlrev_b32_e32 v23, 16, v23
	v_pk_mul_f32 v[42:43], v[22:23], v[22:23]
	s_waitcnt vmcnt(0)
	v_lshlrev_b32_e32 v25, 16, v24
	v_lshlrev_b32_e32 v24, 16, v44
	v_pk_mul_f32 v[44:45], v[24:25], v[24:25]
	v_add_f32_e32 v42, v42, v43
	v_add_f32_e32 v42, v42, v44
	v_add_f32_e32 v42, v42, v45
	ds_bpermute_b32 v30, v32, v42
	s_waitcnt lgkmcnt(0)
	v_add_f32_e32 v30, v42, v30
	ds_bpermute_b32 v40, v33, v30
	s_waitcnt lgkmcnt(0)
	v_add_f32_e32 v30, v30, v40
	ds_bpermute_b32 v40, v34, v30
	s_waitcnt lgkmcnt(0)
	v_add_f32_e32 v30, v30, v40
	ds_bpermute_b32 v40, v35, v30
	s_waitcnt lgkmcnt(0)
	v_add_f32_e32 v30, v30, v40
	ds_bpermute_b32 v40, v36, v30
	s_waitcnt lgkmcnt(0)
	v_add_f32_e32 v30, v30, v40
	v_mov_b32_e32 v40, v30
	v_nop
	v_nop
	v_permlane32_swap_b32 v30, v40
	v_mov_b32_e32 v43, v50
	v_pk_add_f32 v[30:31], v[30:31], v[40:41]
	s_nop 0
	v_pk_fma_f32 v[30:31], v[30:31], s[40:41], v[252:253] op_sel_hi:[1,1,0]
	s_nop 0
	v_mul_f32_e32 v40, 0x4b800000, v31
	v_cmp_gt_f32_e64 s[18:19], s67, v31
	v_cmp_gt_f32_e32 vcc, s67, v30
	s_nop 0
	v_cndmask_b32_e64 v31, v31, v40, s[18:19]
	v_rsq_f32_e32 v31, v31
	s_nop 0
	v_mul_f32_e32 v40, 0x45800000, v31
	v_cndmask_b32_e64 v40, v31, v40, s[18:19]
	v_mul_f32_e32 v0, v40, v0
	v_mul_f32_e32 v31, 0x4b800000, v30
	v_cndmask_b32_e32 v30, v30, v31, vcc
	v_rsq_f32_e32 v41, v30
	v_lshl_add_u64 v[30:31], s[26:27], 0, v[14:15]
	s_mov_b32 s18, 0xecac000
	v_add_co_u32_e64 v30, s[18:19], s18, v30
	v_mul_f32_e32 v42, 0x45800000, v41
	s_nop 0
	v_addc_co_u32_e64 v31, s[18:19], 0, v31, s[18:19]
	v_mul_f32_e32 v0, v43, v0
	v_bfe_u32 v43, v0, 16, 1
	v_add3_u32 v0, v0, v43, s44
	v_mov_b32_e32 v43, v51
	s_nop 0
	global_store_short_d16_hi v[30:31], v0, off offset:256
	v_mul_f32_e32 v0, v40, v46
	v_mul_f32_e32 v0, v43, v0
	v_bfe_u32 v43, v0, 16, 1
	v_add3_u32 v0, v0, v43, s44
	global_store_short_d16_hi v[30:31], v0, off offset:384
	v_mul_f32_e32 v0, v40, v28
	v_mov_b32_e32 v28, v52
	v_mul_f32_e32 v0, v0, v28
	v_bfe_u32 v28, v0, 16, 1
	v_add3_u32 v0, v0, v28, s44
	v_mov_b32_e32 v28, v53
	s_nop 0
	global_store_short_d16_hi v[30:31], v0, off offset:512
	v_mul_f32_e32 v0, v40, v29
	v_mul_f32_e32 v0, v0, v28
	v_bfe_u32 v28, v0, 16, 1
	v_add3_u32 v0, v0, v28, s44
	global_store_short_d16_hi v[30:31], v0, off offset:640
	v_mul_f32_e32 v0, v40, v26
	v_mov_b32_e32 v26, v54
	v_mul_f32_e32 v0, v0, v26
	v_bfe_u32 v26, v0, 16, 1
	v_add3_u32 v0, v0, v26, s44
	v_mov_b32_e32 v26, v55
	s_nop 0
	global_store_short_d16_hi v[30:31], v0, off offset:768
	v_mul_f32_e32 v0, v40, v27
	v_cndmask_b32_e32 v40, v41, v42, vcc
	v_mov_b32_e32 v41, v56
	v_mul_f32_e32 v22, v40, v22
	v_mul_f32_e32 v0, v0, v26
	v_bfe_u32 v26, v0, 16, 1
	v_add3_u32 v0, v0, v26, s44
	global_store_short_d16_hi v[30:31], v0, off offset:896
	v_lshlrev_b64 v[26:27], 9, v[20:21]
	v_ashrrev_i32_e32 v0, 7, v2
	v_lshl_add_u64 v[28:29], v[6:7], 0, v[26:27]
	v_and_or_b32 v26, v0, -2, v5
	v_ashrrev_i32_e32 v27, 31, v26
	v_and_b32_e32 v0, 0xff00, v39
	v_lshlrev_b64 v[30:31], 18, v[26:27]
	v_lshl_add_u64 v[30:31], s[2:3], 0, v[30:31]
	v_lshlrev_b32_e32 v0, 2, v0
	v_mul_f32_e32 v22, v22, v41
	v_lshl_add_u64 v[30:31], v[30:31], 0, v[0:1]
	v_lshlrev_b32_e32 v0, 2, v4
	v_bfe_u32 v41, v22, 16, 1
	v_lshl_add_u64 v[30:31], v[30:31], 0, v[0:1]
	v_add3_u32 v41, v22, v41, s44
	global_store_short_d16_hi v[28:29], v41, off
	s_and_saveexec_b64 s[18:19], s[14:15]
	s_cbranch_execz .LBB0_262
	global_store_dword v[30:31], v22, off
.LBB0_262:
	s_or_b64 exec, exec, s[18:19]
	v_mov_b32_e32 v22, v57
	v_mul_f32_e32 v23, v40, v23
	v_mul_f32_e32 v22, v23, v22
	v_bfe_u32 v23, v22, 16, 1
	v_add3_u32 v23, v22, v23, s44
	global_store_short_d16_hi v[28:29], v23, off offset:128
	s_and_saveexec_b64 s[18:19], s[14:15]
	s_cbranch_execz .LBB0_264
	global_store_dword v[30:31], v22, off offset:256
.LBB0_264:
	s_or_b64 exec, exec, s[18:19]
	v_mov_b32_e32 v22, v58
	v_mul_f32_e32 v23, v40, v24
	v_mul_f32_e32 v22, v23, v22
	v_bfe_u32 v23, v22, 16, 1
	v_add3_u32 v23, v22, v23, s44
	global_store_short_d16_hi v[28:29], v23, off offset:256
	s_and_saveexec_b64 s[18:19], s[14:15]
	s_cbranch_execz .LBB0_266
	global_store_dword v[30:31], v22, off offset:512
.LBB0_266:
	s_or_b64 exec, exec, s[18:19]
	v_mov_b32_e32 v23, v59
	v_mul_f32_e32 v22, v40, v25
	v_mul_f32_e32 v22, v22, v23
	v_bfe_u32 v23, v22, 16, 1
	v_add3_u32 v23, v22, v23, s44
	global_store_short_d16_hi v[28:29], v23, off offset:384
	s_and_saveexec_b64 s[18:19], s[14:15]
	s_cbranch_execz .LBB0_268
	global_store_dword v[30:31], v22, off offset:768
.LBB0_268:
	s_or_b64 exec, exec, s[18:19]
	v_mov_b32_e32 v23, v60
	v_lshlrev_b32_e32 v22, 16, v23
	s_and_saveexec_b64 s[14:15], s[12:13]
	s_xor_b64 s[12:13], exec, s[14:15]
	s_cbranch_execz .LBB0_272
	ds_bpermute_b32 v0, v36, v22
	s_and_saveexec_b64 s[14:15], s[6:7]
	s_cbranch_execz .LBB0_271
	v_lshrrev_b32_e32 v23, 6, v2
	v_cndmask_b32_e64 v23, v2, v23, s[10:11]
	v_and_b32_e32 v23, 63, v23
	v_cvt_f32_ubyte0_e32 v23, v23
	v_mul_f32_e32 v23, v37, v23
	v_mul_f32_e32 v23, 0.15915494, v23
	v_cos_f32_e32 v24, v23
	v_sin_f32_e32 v23, v23
	v_lshlrev_b64 v[20:21], 6, v[20:21]
	v_lshl_add_u64 v[20:21], v[8:9], 0, v[20:21]
	s_waitcnt lgkmcnt(0)
	v_mul_f32_e32 v0, v23, v0
	v_cndmask_b32_e64 v0, v0, -v0, s[8:9]
	v_fmac_f32_e32 v0, v24, v22
	v_bfe_u32 v22, v0, 16, 1
	v_add3_u32 v0, v0, v22, s44
	global_store_short_d16_hi v[20:21], v0, off

.LBB0_490:
	s_lshl_b64 s[0:1], s[6:7], 2
	s_add_u32 s6, s42, s0
	s_addc_u32 s7, s43, s1
	s_add_u32 s0, s26, 0x20114100
	s_addc_u32 s1, s27, 0
	s_lshl_b32 s8, s79, 5
	s_lshl_b64 s[14:15], s[4:5], 2
	s_add_u32 s4, s6, s14
	s_addc_u32 s5, s7, s15
	s_lshl_b32 s6, s2, 8
	v_lshrrev_b32_e32 v0, 1, v189
	s_or_b32 s6, s6, s8
	v_and_or_b32 v146, v0, 24, s6
	v_ashrrev_i32_e32 v147, 31, v146
	v_lshl_add_u64 v[152:153], v[146:147], 2, s[4:5]
	global_load_dwordx4 v[130:133], v[152:153], off offset:16
	global_load_dwordx4 v[138:141], v[152:153], off
	s_lshl_b32 s16, s78, 8
	s_add_i32 s4, s16, s49
	v_or_b32_e32 v176, s4, v144
	v_ashrrev_i32_e32 v177, 31, v176
	v_lshlrev_b64 v[154:155], 10, v[176:177]
	v_lshl_add_u64 v[148:149], v[154:155], 0, v[146:147]
	s_mov_b64 s[4:5], -1
	s_and_b64 vcc, exec, s[94:95]
	v_lshl_add_u64 v[156:157], v[148:149], 1, s[0:1]
	s_cbranch_vccz .LBB0_492
	v_mov_b32_e32 v190, v156
	v_mov_b32_e32 v191, v157
	s_mov_b64 s[100:101], 0x8000
	global_load_dwordx4 v[192:195], v[190:191], off
	v_lshl_add_u64 v[190:191], v[190:191], 0, s[100:101]
	global_load_dwordx4 v[198:201], v[190:191], off
	v_lshl_add_u64 v[190:191], v[190:191], 0, s[100:101]
	global_load_dwordx4 v[202:205], v[190:191], off
	v_lshl_add_u64 v[190:191], v[190:191], 0, s[100:101]
	global_load_dwordx4 v[206:209], v[190:191], off
	s_mov_b64 s[100:101], 0x28000
	v_lshl_add_u64 v[190:191], v[190:191], 0, s[100:101]
	s_mov_b64 s[100:101], 0x8000
	global_load_dwordx4 v[210:213], v[190:191], off
	v_lshl_add_u64 v[190:191], v[190:191], 0, s[100:101]
	global_load_dwordx4 v[214:217], v[190:191], off
	v_lshl_add_u64 v[190:191], v[190:191], 0, s[100:101]
	global_load_dwordx4 v[220:223], v[190:191], off
	v_lshl_add_u64 v[190:191], v[190:191], 0, s[100:101]
	global_load_dwordx4 v[224:227], v[190:191], off
	v_mov_b32_e32 v190, v156
	v_mov_b32_e32 v191, v157
	global_load_dwordx4 v[228:231], v[190:191], off offset:256
	v_lshl_add_u64 v[190:191], v[190:191], 0, s[100:101]
	global_load_dwordx4 v[232:235], v[190:191], off offset:256
	v_lshl_add_u64 v[190:191], v[190:191], 0, s[100:101]
	global_load_dwordx4 v[236:239], v[190:191], off offset:256
	v_lshl_add_u64 v[190:191], v[190:191], 0, s[100:101]
	global_load_dwordx4 v[240:243], v[190:191], off offset:256
	s_mov_b64 s[100:101], 0x28000
	v_lshl_add_u64 v[190:191], v[190:191], 0, s[100:101]
	s_mov_b64 s[100:101], 0x8000
	global_load_dwordx4 v[244:247], v[190:191], off offset:256
	v_lshl_add_u64 v[190:191], v[190:191], 0, s[100:101]
	global_load_dwordx4 v[248:251], v[190:191], off offset:256
	s_mov_b64 s[4:5], 0
	s_waitcnt vmcnt(13)
	v_cvt_f32_f16_e32 v142, v192
	v_cvt_f32_f16_sdwa v143, v192 dst_sel:DWORD dst_unused:UNUSED_PAD src0_sel:WORD_1
	v_cvt_f32_f16_e32 v144, v193
	v_cvt_f32_f16_sdwa v145, v193 dst_sel:DWORD dst_unused:UNUSED_PAD src0_sel:WORD_1
	v_cvt_f32_f16_e32 v134, v194
	v_cvt_f32_f16_sdwa v135, v194 dst_sel:DWORD dst_unused:UNUSED_PAD src0_sel:WORD_1
	v_cvt_f32_f16_e32 v136, v195
	v_cvt_f32_f16_sdwa v137, v195 dst_sel:DWORD dst_unused:UNUSED_PAD src0_sel:WORD_1
.LBB0_492:
	v_readlane_b32 s36, v255, 14
	s_andn2_b64 vcc, exec, s[4:5]
	v_lshl_add_u64 v[150:151], v[148:149], 2, s[40:41]
	v_readlane_b32 s37, v255, 15
	s_cbranch_vccnz .LBB0_494
	global_load_dwordx4 v[134:137], v[150:151], off offset:16
	global_load_dwordx4 v[142:145], v[150:151], off
	s_waitcnt vmcnt(0)
.LBB0_494:
	s_mov_b32 s19, s18
	s_cmp_lg_u64 s[36:37], 0
	v_pk_mul_f32 v[140:141], s[18:19], v[140:141]
	v_pk_mul_f32 v[186:187], s[28:29], v[138:139]
	v_pk_mul_f32 v[184:185], s[18:19], v[132:133]
	v_pk_mul_f32 v[148:149], s[28:29], v[130:131]
	s_cselect_b64 s[10:11], -1, 0
	s_cmp_eq_u64 s[36:37], 0
	v_pk_fma_f32 v[130:131], v[126:127], v[186:187], v[142:143]
	v_pk_fma_f32 v[138:139], v[128:129], v[140:141], v[144:145]
	v_pk_fma_f32 v[132:133], v[122:123], v[148:149], v[134:135]
	v_pk_fma_f32 v[134:135], v[124:125], v[184:185], v[136:137]
	s_cbranch_scc1 .LBB0_496
	v_cvt_pk_f16_f32 v122, v130, v131
	v_cvt_pk_f16_f32 v123, v138, v139
	v_cvt_pk_f16_f32 v124, v132, v133
	v_cvt_pk_f16_f32 v125, v134, v135
	global_store_dwordx4 v[156:157], v[122:125], off
.LBB0_496:
	s_nop 1
	v_or_b32_e32 v122, 16, v176
	v_ashrrev_i32_e32 v123, 31, v122
	v_lshlrev_b64 v[160:161], 10, v[122:123]
	v_lshl_add_u64 v[142:143], v[160:161], 0, v[146:147]
	v_cndmask_b32_e64 v0, 0, 1, s[94:95]
	s_mov_b64 s[4:5], -1
	v_cmp_ne_u32_e64 s[8:9], 1, v0
	s_andn2_b64 vcc, exec, s[94:95]
	v_lshl_add_u64 v[136:137], v[142:143], 1, s[0:1]
	s_cbranch_vccnz .LBB0_498
	s_mov_b64 s[4:5], 0
	s_waitcnt vmcnt(12)
	v_cvt_f32_f16_e32 v126, v198
	v_cvt_f32_f16_sdwa v127, v198 dst_sel:DWORD dst_unused:UNUSED_PAD src0_sel:WORD_1
	v_cvt_f32_f16_e32 v128, v199
	v_cvt_f32_f16_sdwa v129, v199 dst_sel:DWORD dst_unused:UNUSED_PAD src0_sel:WORD_1
	v_cvt_f32_f16_e32 v122, v200
	v_cvt_f32_f16_sdwa v123, v200 dst_sel:DWORD dst_unused:UNUSED_PAD src0_sel:WORD_1
	v_cvt_f32_f16_e32 v124, v201
	v_cvt_f32_f16_sdwa v125, v201 dst_sel:DWORD dst_unused:UNUSED_PAD src0_sel:WORD_1
.LBB0_498:
	v_readlane_b32 s34, v255, 9
	s_andn2_b64 vcc, exec, s[4:5]
	v_lshl_add_u64 v[156:157], v[142:143], 2, s[40:41]
	v_readlane_b32 s35, v255, 10
	s_cbranch_vccnz .LBB0_500
	global_load_dwordx4 v[122:125], v[156:157], off offset:16
	global_load_dwordx4 v[126:129], v[156:157], off
	s_waitcnt vmcnt(0)
.LBB0_500:
	v_cndmask_b32_e64 v0, 0, 1, s[10:11]
	v_pk_fma_f32 v[128:129], v[120:121], v[140:141], v[128:129]
	v_pk_fma_f32 v[126:127], v[118:119], v[186:187], v[126:127]
	v_pk_fma_f32 v[124:125], v[116:117], v[184:185], v[124:125]
	v_cmp_ne_u32_e64 s[6:7], 1, v0
	s_andn2_b64 vcc, exec, s[10:11]
	v_pk_fma_f32 v[122:123], v[114:115], v[148:149], v[122:123]
	s_cbranch_vccnz .LBB0_502
	v_cvt_pk_f16_f32 v114, v126, v127
	v_cvt_pk_f16_f32 v115, v128, v129
	v_cvt_pk_f16_f32 v116, v122, v123
	v_cvt_pk_f16_f32 v117, v124, v125
	global_store_dwordx4 v[136:137], v[114:117], off
.LBB0_502:
	s_nop 1
	v_or_b32_e32 v114, 32, v176
	v_ashrrev_i32_e32 v115, 31, v114
	v_lshlrev_b64 v[166:167], 10, v[114:115]
	v_lshl_add_u64 v[142:143], v[166:167], 0, v[146:147]
	s_mov_b64 s[4:5], -1
	s_and_b64 vcc, exec, s[8:9]
	v_lshl_add_u64 v[136:137], v[142:143], 1, s[0:1]
	s_cbranch_vccnz .LBB0_504
	s_mov_b64 s[4:5], 0
	s_waitcnt vmcnt(11)
	v_cvt_f32_f16_e32 v118, v202
	v_cvt_f32_f16_sdwa v119, v202 dst_sel:DWORD dst_unused:UNUSED_PAD src0_sel:WORD_1
	v_cvt_f32_f16_e32 v120, v203
	v_cvt_f32_f16_sdwa v121, v203 dst_sel:DWORD dst_unused:UNUSED_PAD src0_sel:WORD_1
	v_cvt_f32_f16_e32 v114, v204
	v_cvt_f32_f16_sdwa v115, v204 dst_sel:DWORD dst_unused:UNUSED_PAD src0_sel:WORD_1
	v_cvt_f32_f16_e32 v116, v205
	v_cvt_f32_f16_sdwa v117, v205 dst_sel:DWORD dst_unused:UNUSED_PAD src0_sel:WORD_1
	s_mov_b64 s[100:101], 0x8000
	v_lshl_add_u64 v[190:191], v[190:191], 0, s[100:101]
	global_load_dwordx4 v[192:195], v[190:191], off offset:256
	v_lshl_add_u64 v[190:191], v[190:191], 0, s[100:101]
	global_load_dwordx4 v[198:201], v[190:191], off offset:256
.LBB0_504:
	s_andn2_b64 vcc, exec, s[4:5]
	v_lshl_add_u64 v[158:159], v[142:143], 2, s[40:41]
	s_cbranch_vccnz .LBB0_506
	global_load_dwordx4 v[114:117], v[158:159], off offset:16
	global_load_dwordx4 v[118:121], v[158:159], off
	s_waitcnt vmcnt(0)
.LBB0_506:
	v_pk_fma_f32 v[120:121], v[112:113], v[140:141], v[120:121]
	v_pk_fma_f32 v[118:119], v[110:111], v[186:187], v[118:119]
	v_pk_fma_f32 v[116:117], v[108:109], v[184:185], v[116:117]
	s_and_b64 vcc, exec, s[6:7]
	v_pk_fma_f32 v[114:115], v[106:107], v[148:149], v[114:115]
	s_cbranch_vccnz .LBB0_508
	v_cvt_pk_f16_f32 v106, v118, v119
	v_cvt_pk_f16_f32 v107, v120, v121
	v_cvt_pk_f16_f32 v108, v114, v115
	v_cvt_pk_f16_f32 v109, v116, v117
	global_store_dwordx4 v[136:137], v[106:109], off
.LBB0_508:
	s_nop 1
	v_or_b32_e32 v106, 48, v176
	v_ashrrev_i32_e32 v107, 31, v106
	v_lshlrev_b64 v[170:171], 10, v[106:107]
	v_lshl_add_u64 v[142:143], v[170:171], 0, v[146:147]
	s_mov_b64 s[4:5], -1
	s_and_b64 vcc, exec, s[8:9]
	v_lshl_add_u64 v[136:137], v[142:143], 1, s[0:1]
	s_cbranch_vccnz .LBB0_510
	s_mov_b64 s[4:5], 0
	s_waitcnt vmcnt(12)
	v_cvt_f32_f16_e32 v110, v206
	v_cvt_f32_f16_sdwa v111, v206 dst_sel:DWORD dst_unused:UNUSED_PAD src0_sel:WORD_1
	v_cvt_f32_f16_e32 v112, v207
	v_cvt_f32_f16_sdwa v113, v207 dst_sel:DWORD dst_unused:UNUSED_PAD src0_sel:WORD_1
	v_cvt_f32_f16_e32 v106, v208
	v_cvt_f32_f16_sdwa v107, v208 dst_sel:DWORD dst_unused:UNUSED_PAD src0_sel:WORD_1
	v_cvt_f32_f16_e32 v108, v209
	v_cvt_f32_f16_sdwa v109, v209 dst_sel:DWORD dst_unused:UNUSED_PAD src0_sel:WORD_1
.LBB0_510:
	s_andn2_b64 vcc, exec, s[4:5]
	v_lshl_add_u64 v[162:163], v[142:143], 2, s[40:41]
	s_cbranch_vccnz .LBB0_512
	global_load_dwordx4 v[106:109], v[162:163], off offset:16
	global_load_dwordx4 v[110:113], v[162:163], off
	s_waitcnt vmcnt(0)
.LBB0_512:
	v_pk_fma_f32 v[112:113], v[104:105], v[140:141], v[112:113]
	v_pk_fma_f32 v[110:111], v[102:103], v[186:187], v[110:111]
	v_pk_fma_f32 v[108:109], v[100:101], v[184:185], v[108:109]
	s_and_b64 vcc, exec, s[6:7]
	v_pk_fma_f32 v[106:107], v[98:99], v[148:149], v[106:107]
	s_cbranch_vccnz .LBB0_514
	v_cvt_pk_f16_f32 v98, v110, v111
	v_cvt_pk_f16_f32 v99, v112, v113
	v_cvt_pk_f16_f32 v100, v106, v107
	v_cvt_pk_f16_f32 v101, v108, v109
	global_store_dwordx4 v[136:137], v[98:101], off
.LBB0_514:
	s_nop 1
	v_lshlrev_b64 v[98:99], 10, v[176:177]
	v_lshl_add_u64 v[174:175], v[98:99], 0, s[56:57]
	v_lshl_add_u64 v[142:143], v[174:175], 0, v[146:147]
	s_mov_b64 s[4:5], -1
	s_and_b64 vcc, exec, s[8:9]
	v_lshl_add_u64 v[136:137], v[142:143], 1, s[0:1]
	s_cbranch_vccnz .LBB0_516
	s_mov_b64 s[4:5], 0
	s_waitcnt vmcnt(11)
	v_cvt_f32_f16_e32 v102, v210
	v_cvt_f32_f16_sdwa v103, v210 dst_sel:DWORD dst_unused:UNUSED_PAD src0_sel:WORD_1
	v_cvt_f32_f16_e32 v104, v211
	v_cvt_f32_f16_sdwa v105, v211 dst_sel:DWORD dst_unused:UNUSED_PAD src0_sel:WORD_1
	v_cvt_f32_f16_e32 v98, v212
	v_cvt_f32_f16_sdwa v99, v212 dst_sel:DWORD dst_unused:UNUSED_PAD src0_sel:WORD_1
	v_cvt_f32_f16_e32 v100, v213
	v_cvt_f32_f16_sdwa v101, v213 dst_sel:DWORD dst_unused:UNUSED_PAD src0_sel:WORD_1
.LBB0_516:
	s_andn2_b64 vcc, exec, s[4:5]
	v_lshl_add_u64 v[164:165], v[142:143], 2, s[40:41]
	s_cbranch_vccnz .LBB0_518
	global_load_dwordx4 v[98:101], v[164:165], off offset:16
	global_load_dwordx4 v[102:105], v[164:165], off
	s_waitcnt vmcnt(0)
.LBB0_518:
	v_pk_fma_f32 v[104:105], v[96:97], v[140:141], v[104:105]
	v_pk_fma_f32 v[102:103], v[94:95], v[186:187], v[102:103]
	v_pk_fma_f32 v[100:101], v[92:93], v[184:185], v[100:101]
	s_and_b64 vcc, exec, s[6:7]
	v_pk_fma_f32 v[98:99], v[90:91], v[148:149], v[98:99]
	s_cbranch_vccnz .LBB0_520
	v_cvt_pk_f16_f32 v90, v102, v103
	v_cvt_pk_f16_f32 v91, v104, v105
	v_cvt_pk_f16_f32 v92, v98, v99
	v_cvt_pk_f16_f32 v93, v100, v101
	global_store_dwordx4 v[136:137], v[90:93], off
.LBB0_520:
	s_nop 1
	v_lshlrev_b64 v[90:91], 10, v[176:177]
	s_mov_b64 s[4:5], 0x24000
	v_lshl_add_u64 v[178:179], v[90:91], 0, s[4:5]
	v_lshl_add_u64 v[142:143], v[178:179], 0, v[146:147]
	s_mov_b64 s[4:5], -1
	s_and_b64 vcc, exec, s[8:9]
	v_lshl_add_u64 v[136:137], v[142:143], 1, s[0:1]
	s_cbranch_vccnz .LBB0_522
	s_mov_b64 s[4:5], 0
	s_waitcnt vmcnt(10)
	v_cvt_f32_f16_e32 v94, v214
	v_cvt_f32_f16_sdwa v95, v214 dst_sel:DWORD dst_unused:UNUSED_PAD src0_sel:WORD_1
	v_cvt_f32_f16_e32 v96, v215
	v_cvt_f32_f16_sdwa v97, v215 dst_sel:DWORD dst_unused:UNUSED_PAD src0_sel:WORD_1
	v_cvt_f32_f16_e32 v90, v216
	v_cvt_f32_f16_sdwa v91, v216 dst_sel:DWORD dst_unused:UNUSED_PAD src0_sel:WORD_1
	v_cvt_f32_f16_e32 v92, v217
	v_cvt_f32_f16_sdwa v93, v217 dst_sel:DWORD dst_unused:UNUSED_PAD src0_sel:WORD_1
.LBB0_522:
	s_andn2_b64 vcc, exec, s[4:5]
	v_lshl_add_u64 v[168:169], v[142:143], 2, s[40:41]
	s_cbranch_vccnz .LBB0_524
	global_load_dwordx4 v[90:93], v[168:169], off offset:16
	global_load_dwordx4 v[94:97], v[168:169], off
	s_waitcnt vmcnt(0)
.LBB0_524:
	v_pk_fma_f32 v[96:97], v[88:89], v[140:141], v[96:97]
	v_pk_fma_f32 v[94:95], v[86:87], v[186:187], v[94:95]
	v_pk_fma_f32 v[92:93], v[84:85], v[184:185], v[92:93]
	s_and_b64 vcc, exec, s[6:7]
	v_pk_fma_f32 v[90:91], v[82:83], v[148:149], v[90:91]
	s_cbranch_vccnz .LBB0_526
	v_cvt_pk_f16_f32 v82, v94, v95
	v_cvt_pk_f16_f32 v83, v96, v97
	v_cvt_pk_f16_f32 v84, v90, v91
	v_cvt_pk_f16_f32 v85, v92, v93
	global_store_dwordx4 v[136:137], v[82:85], off
.LBB0_526:
	s_nop 1
	v_lshlrev_b64 v[82:83], 10, v[176:177]
	s_mov_b64 s[4:5], 0x28000
	v_lshl_add_u64 v[180:181], v[82:83], 0, s[4:5]
	v_lshl_add_u64 v[136:137], v[180:181], 0, v[146:147]
	s_mov_b64 s[4:5], -1
	s_and_b64 vcc, exec, s[8:9]
	v_lshl_add_u64 v[142:143], v[136:137], 1, s[0:1]
	s_cbranch_vccnz .LBB0_528
	s_mov_b64 s[4:5], 0
	s_waitcnt vmcnt(9)
	v_cvt_f32_f16_e32 v86, v220
	v_cvt_f32_f16_sdwa v87, v220 dst_sel:DWORD dst_unused:UNUSED_PAD src0_sel:WORD_1
	v_cvt_f32_f16_e32 v88, v221
	v_cvt_f32_f16_sdwa v89, v221 dst_sel:DWORD dst_unused:UNUSED_PAD src0_sel:WORD_1
	v_cvt_f32_f16_e32 v82, v222
	v_cvt_f32_f16_sdwa v83, v222 dst_sel:DWORD dst_unused:UNUSED_PAD src0_sel:WORD_1
	v_cvt_f32_f16_e32 v84, v223
	v_cvt_f32_f16_sdwa v85, v223 dst_sel:DWORD dst_unused:UNUSED_PAD src0_sel:WORD_1
.LBB0_528:
	s_andn2_b64 vcc, exec, s[4:5]
	v_lshl_add_u64 v[172:173], v[136:137], 2, s[40:41]
	s_cbranch_vccnz .LBB0_530
	global_load_dwordx4 v[82:85], v[172:173], off offset:16
	global_load_dwordx4 v[86:89], v[172:173], off
	s_waitcnt vmcnt(0)
.LBB0_530:
	v_pk_fma_f32 v[88:89], v[80:81], v[140:141], v[88:89]
	v_pk_fma_f32 v[86:87], v[78:79], v[186:187], v[86:87]
	v_pk_fma_f32 v[84:85], v[76:77], v[184:185], v[84:85]
	s_and_b64 vcc, exec, s[6:7]
	v_pk_fma_f32 v[136:137], v[74:75], v[148:149], v[82:83]
	s_cbranch_vccnz .LBB0_532
	v_cvt_pk_f16_f32 v74, v86, v87
	v_cvt_pk_f16_f32 v75, v88, v89
	v_cvt_pk_f16_f32 v76, v136, v137
	v_cvt_pk_f16_f32 v77, v84, v85
	global_store_dwordx4 v[142:143], v[74:77], off
.LBB0_532:
	s_nop 1
	v_lshlrev_b64 v[74:75], 10, v[176:177]
	s_mov_b64 s[4:5], 0x2c000
	v_lshl_add_u64 v[182:183], v[74:75], 0, s[4:5]
	v_lshl_add_u64 v[142:143], v[182:183], 0, v[146:147]
	s_mov_b64 s[4:5], -1
	s_and_b64 vcc, exec, s[8:9]
	v_lshl_add_u64 v[82:83], v[142:143], 1, s[0:1]
	s_cbranch_vccnz .LBB0_534
	s_mov_b64 s[4:5], 0
	s_waitcnt vmcnt(8)
	v_cvt_f32_f16_e32 v78, v224
	v_cvt_f32_f16_sdwa v79, v224 dst_sel:DWORD dst_unused:UNUSED_PAD src0_sel:WORD_1
	v_cvt_f32_f16_e32 v80, v225
	v_cvt_f32_f16_sdwa v81, v225 dst_sel:DWORD dst_unused:UNUSED_PAD src0_sel:WORD_1
	v_cvt_f32_f16_e32 v74, v226
	v_cvt_f32_f16_sdwa v75, v226 dst_sel:DWORD dst_unused:UNUSED_PAD src0_sel:WORD_1
	v_cvt_f32_f16_e32 v76, v227
	v_cvt_f32_f16_sdwa v77, v227 dst_sel:DWORD dst_unused:UNUSED_PAD src0_sel:WORD_1
.LBB0_534:
	s_andn2_b64 vcc, exec, s[4:5]
	v_lshl_add_u64 v[176:177], v[142:143], 2, s[40:41]
	s_cbranch_vccnz .LBB0_536
	global_load_dwordx4 v[74:77], v[176:177], off offset:16
	global_load_dwordx4 v[78:81], v[176:177], off
	s_waitcnt vmcnt(0)
.LBB0_536:
	v_pk_fma_f32 v[140:141], v[72:73], v[140:141], v[80:81]
	v_pk_fma_f32 v[144:145], v[70:71], v[186:187], v[78:79]
	v_pk_fma_f32 v[142:143], v[68:69], v[184:185], v[76:77]
	s_and_b64 vcc, exec, s[6:7]
	v_pk_fma_f32 v[148:149], v[66:67], v[148:149], v[74:75]
	s_cbranch_vccnz .LBB0_538
	v_cvt_pk_f16_f32 v66, v144, v145
	v_cvt_pk_f16_f32 v67, v140, v141
	v_cvt_pk_f16_f32 v68, v148, v149
	v_cvt_pk_f16_f32 v69, v142, v143
	global_store_dwordx4 v[82:83], v[66:69], off
.LBB0_538:
	global_load_dwordx4 v[70:73], v[152:153], off offset:528
	global_load_dwordx4 v[78:81], v[152:153], off offset:512
	v_or_b32_e32 v82, 0x80, v146
	v_mov_b32_e32 v83, v147
	v_lshl_add_u64 v[66:67], v[154:155], 0, v[82:83]
	s_mov_b64 s[4:5], -1
	s_and_b64 vcc, exec, s[8:9]
	v_lshl_add_u64 v[186:187], v[66:67], 1, s[0:1]
	s_cbranch_vccnz .LBB0_540
	s_mov_b64 s[4:5], 0
	s_waitcnt vmcnt(0)
	v_cvt_f32_f16_e32 v74, v228
	v_cvt_f32_f16_sdwa v75, v228 dst_sel:DWORD dst_unused:UNUSED_PAD src0_sel:WORD_1
	v_cvt_f32_f16_e32 v76, v229
	v_cvt_f32_f16_sdwa v77, v229 dst_sel:DWORD dst_unused:UNUSED_PAD src0_sel:WORD_1
	v_cvt_f32_f16_e32 v66, v230
	v_cvt_f32_f16_sdwa v67, v230 dst_sel:DWORD dst_unused:UNUSED_PAD src0_sel:WORD_1
	v_cvt_f32_f16_e32 v68, v231
	v_cvt_f32_f16_sdwa v69, v231 dst_sel:DWORD dst_unused:UNUSED_PAD src0_sel:WORD_1
.LBB0_540:
	s_andn2_b64 vcc, exec, s[4:5]
	s_cbranch_vccnz .LBB0_542
	global_load_dwordx4 v[66:69], v[150:151], off offset:528
	global_load_dwordx4 v[74:77], v[150:151], off offset:512
	s_waitcnt vmcnt(0)
.LBB0_542:
	s_mov_b32 s19, s18
	v_pk_mul_f32 v[150:151], s[18:19], v[80:81]
	v_pk_mul_f32 v[154:155], s[28:29], v[78:79]
	v_pk_mul_f32 v[152:153], s[18:19], v[72:73]
	v_pk_mul_f32 v[184:185], s[28:29], v[70:71]
	v_pk_fma_f32 v[70:71], v[62:63], v[154:155], v[74:75]
	v_pk_fma_f32 v[72:73], v[64:65], v[150:151], v[76:77]
	v_pk_fma_f32 v[66:67], v[58:59], v[184:185], v[66:67]
	s_and_b64 vcc, exec, s[6:7]
	v_pk_fma_f32 v[68:69], v[60:61], v[152:153], v[68:69]
	s_cbranch_vccnz .LBB0_544
	v_cvt_pk_f16_f32 v58, v70, v71
	v_cvt_pk_f16_f32 v59, v72, v73
	v_cvt_pk_f16_f32 v60, v66, v67
	v_cvt_pk_f16_f32 v61, v68, v69
	global_store_dwordx4 v[186:187], v[58:61], off
.LBB0_544:
	s_nop 1
	v_lshl_add_u64 v[58:59], v[160:161], 0, v[82:83]
	s_mov_b64 s[4:5], -1
	s_and_b64 vcc, exec, s[8:9]
	v_lshl_add_u64 v[74:75], v[58:59], 1, s[0:1]
	s_cbranch_vccnz .LBB0_546
	s_mov_b64 s[4:5], 0
	v_cvt_f32_f16_e32 v62, v232
	v_cvt_f32_f16_sdwa v63, v232 dst_sel:DWORD dst_unused:UNUSED_PAD src0_sel:WORD_1
	v_cvt_f32_f16_e32 v64, v233
	v_cvt_f32_f16_sdwa v65, v233 dst_sel:DWORD dst_unused:UNUSED_PAD src0_sel:WORD_1
	v_cvt_f32_f16_e32 v58, v234
	v_cvt_f32_f16_sdwa v59, v234 dst_sel:DWORD dst_unused:UNUSED_PAD src0_sel:WORD_1
	v_cvt_f32_f16_e32 v60, v235
	v_cvt_f32_f16_sdwa v61, v235 dst_sel:DWORD dst_unused:UNUSED_PAD src0_sel:WORD_1
.LBB0_546:
	s_andn2_b64 vcc, exec, s[4:5]
	s_cbranch_vccnz .LBB0_548
	global_load_dwordx4 v[58:61], v[156:157], off offset:528
	global_load_dwordx4 v[62:65], v[156:157], off offset:512
	s_waitcnt vmcnt(0)
.LBB0_548:
	v_pk_fma_f32 v[64:65], v[56:57], v[150:151], v[64:65]
	v_pk_fma_f32 v[62:63], v[54:55], v[154:155], v[62:63]
	v_pk_fma_f32 v[60:61], v[52:53], v[152:153], v[60:61]
	s_and_b64 vcc, exec, s[6:7]
	v_pk_fma_f32 v[58:59], v[50:51], v[184:185], v[58:59]
	s_cbranch_vccnz .LBB0_550
	v_cvt_pk_f16_f32 v50, v62, v63
	v_cvt_pk_f16_f32 v51, v64, v65
	v_cvt_pk_f16_f32 v52, v58, v59
	v_cvt_pk_f16_f32 v53, v60, v61
	global_store_dwordx4 v[74:75], v[50:53], off
.LBB0_550:
	s_nop 1
	v_lshl_add_u64 v[50:51], v[166:167], 0, v[82:83]
	s_mov_b64 s[4:5], -1
	s_and_b64 vcc, exec, s[8:9]
	v_lshl_add_u64 v[74:75], v[50:51], 1, s[0:1]
	s_cbranch_vccnz .LBB0_552
	s_mov_b64 s[4:5], 0
	v_cvt_f32_f16_e32 v54, v236
	v_cvt_f32_f16_sdwa v55, v236 dst_sel:DWORD dst_unused:UNUSED_PAD src0_sel:WORD_1
	v_cvt_f32_f16_e32 v56, v237
	v_cvt_f32_f16_sdwa v57, v237 dst_sel:DWORD dst_unused:UNUSED_PAD src0_sel:WORD_1
	v_cvt_f32_f16_e32 v50, v238
	v_cvt_f32_f16_sdwa v51, v238 dst_sel:DWORD dst_unused:UNUSED_PAD src0_sel:WORD_1
	v_cvt_f32_f16_e32 v52, v239
	v_cvt_f32_f16_sdwa v53, v239 dst_sel:DWORD dst_unused:UNUSED_PAD src0_sel:WORD_1
.LBB0_552:
	s_andn2_b64 vcc, exec, s[4:5]
	s_cbranch_vccnz .LBB0_554
	global_load_dwordx4 v[50:53], v[158:159], off offset:528
	global_load_dwordx4 v[54:57], v[158:159], off offset:512
	s_waitcnt vmcnt(0)
.LBB0_554:
	v_pk_fma_f32 v[56:57], v[48:49], v[150:151], v[56:57]
	v_pk_fma_f32 v[54:55], v[46:47], v[154:155], v[54:55]
	v_pk_fma_f32 v[52:53], v[44:45], v[152:153], v[52:53]
	s_and_b64 vcc, exec, s[6:7]
	v_pk_fma_f32 v[50:51], v[42:43], v[184:185], v[50:51]
	s_cbranch_vccnz .LBB0_556
	v_cvt_pk_f16_f32 v42, v54, v55
	v_cvt_pk_f16_f32 v43, v56, v57
	v_cvt_pk_f16_f32 v44, v50, v51
	v_cvt_pk_f16_f32 v45, v52, v53
	global_store_dwordx4 v[74:75], v[42:45], off
.LBB0_556:
	s_nop 1
	v_lshl_add_u64 v[42:43], v[170:171], 0, v[82:83]
	s_mov_b64 s[4:5], -1
	s_and_b64 vcc, exec, s[8:9]
	v_lshl_add_u64 v[74:75], v[42:43], 1, s[0:1]
	s_cbranch_vccnz .LBB0_558
	s_mov_b64 s[4:5], 0
	v_cvt_f32_f16_e32 v46, v240
	v_cvt_f32_f16_sdwa v47, v240 dst_sel:DWORD dst_unused:UNUSED_PAD src0_sel:WORD_1
	v_cvt_f32_f16_e32 v48, v241
	v_cvt_f32_f16_sdwa v49, v241 dst_sel:DWORD dst_unused:UNUSED_PAD src0_sel:WORD_1
	v_cvt_f32_f16_e32 v42, v242
	v_cvt_f32_f16_sdwa v43, v242 dst_sel:DWORD dst_unused:UNUSED_PAD src0_sel:WORD_1
	v_cvt_f32_f16_e32 v44, v243
	v_cvt_f32_f16_sdwa v45, v243 dst_sel:DWORD dst_unused:UNUSED_PAD src0_sel:WORD_1
.LBB0_558:
	s_andn2_b64 vcc, exec, s[4:5]
	s_cbranch_vccnz .LBB0_560
	global_load_dwordx4 v[42:45], v[162:163], off offset:528
	global_load_dwordx4 v[46:49], v[162:163], off offset:512
	s_waitcnt vmcnt(0)
.LBB0_560:
	v_pk_fma_f32 v[48:49], v[40:41], v[150:151], v[48:49]
	v_pk_fma_f32 v[46:47], v[38:39], v[154:155], v[46:47]
	v_pk_fma_f32 v[44:45], v[36:37], v[152:153], v[44:45]
	s_and_b64 vcc, exec, s[6:7]
	v_pk_fma_f32 v[42:43], v[34:35], v[184:185], v[42:43]
	s_cbranch_vccnz .LBB0_562
	v_cvt_pk_f16_f32 v34, v46, v47
	v_cvt_pk_f16_f32 v35, v48, v49
	v_cvt_pk_f16_f32 v36, v42, v43
	v_cvt_pk_f16_f32 v37, v44, v45
	global_store_dwordx4 v[74:75], v[34:37], off
.LBB0_562:
	s_nop 1
	v_lshl_add_u64 v[34:35], v[174:175], 0, v[82:83]
	s_mov_b64 s[4:5], -1
	s_and_b64 vcc, exec, s[8:9]
	v_lshl_add_u64 v[74:75], v[34:35], 1, s[0:1]
	s_cbranch_vccnz .LBB0_564
	s_mov_b64 s[4:5], 0
	v_cvt_f32_f16_e32 v38, v244
	v_cvt_f32_f16_sdwa v39, v244 dst_sel:DWORD dst_unused:UNUSED_PAD src0_sel:WORD_1
	v_cvt_f32_f16_e32 v40, v245
	v_cvt_f32_f16_sdwa v41, v245 dst_sel:DWORD dst_unused:UNUSED_PAD src0_sel:WORD_1
	v_cvt_f32_f16_e32 v34, v246
	v_cvt_f32_f16_sdwa v35, v246 dst_sel:DWORD dst_unused:UNUSED_PAD src0_sel:WORD_1
	v_cvt_f32_f16_e32 v36, v247
	v_cvt_f32_f16_sdwa v37, v247 dst_sel:DWORD dst_unused:UNUSED_PAD src0_sel:WORD_1
.LBB0_564:
	s_andn2_b64 vcc, exec, s[4:5]
	s_cbranch_vccnz .LBB0_566
	global_load_dwordx4 v[34:37], v[164:165], off offset:528
	global_load_dwordx4 v[38:41], v[164:165], off offset:512
	s_waitcnt vmcnt(0)
.LBB0_566:
	v_pk_fma_f32 v[40:41], v[32:33], v[150:151], v[40:41]
	v_pk_fma_f32 v[38:39], v[30:31], v[154:155], v[38:39]
	v_pk_fma_f32 v[36:37], v[28:29], v[152:153], v[36:37]
	s_and_b64 vcc, exec, s[6:7]
	v_pk_fma_f32 v[34:35], v[26:27], v[184:185], v[34:35]
	s_cbranch_vccnz .LBB0_568
	v_cvt_pk_f16_f32 v26, v38, v39
	v_cvt_pk_f16_f32 v27, v40, v41
	v_cvt_pk_f16_f32 v28, v34, v35
	v_cvt_pk_f16_f32 v29, v36, v37
	global_store_dwordx4 v[74:75], v[26:29], off
.LBB0_568:
	s_nop 1
	v_lshl_add_u64 v[26:27], v[178:179], 0, v[82:83]
	s_mov_b64 s[4:5], -1
	s_and_b64 vcc, exec, s[8:9]
	v_lshl_add_u64 v[74:75], v[26:27], 1, s[0:1]
	s_cbranch_vccnz .LBB0_570
	s_mov_b64 s[4:5], 0
	v_cvt_f32_f16_e32 v30, v248
	v_cvt_f32_f16_sdwa v31, v248 dst_sel:DWORD dst_unused:UNUSED_PAD src0_sel:WORD_1
	v_cvt_f32_f16_e32 v32, v249
	v_cvt_f32_f16_sdwa v33, v249 dst_sel:DWORD dst_unused:UNUSED_PAD src0_sel:WORD_1
	v_cvt_f32_f16_e32 v26, v250
	v_cvt_f32_f16_sdwa v27, v250 dst_sel:DWORD dst_unused:UNUSED_PAD src0_sel:WORD_1
	v_cvt_f32_f16_e32 v28, v251
	v_cvt_f32_f16_sdwa v29, v251 dst_sel:DWORD dst_unused:UNUSED_PAD src0_sel:WORD_1
.LBB0_570:
	s_andn2_b64 vcc, exec, s[4:5]
	s_cbranch_vccnz .LBB0_572
	global_load_dwordx4 v[26:29], v[168:169], off offset:528
	global_load_dwordx4 v[30:33], v[168:169], off offset:512
	s_waitcnt vmcnt(0)
.LBB0_572:
	v_pk_fma_f32 v[32:33], v[24:25], v[150:151], v[32:33]
	v_pk_fma_f32 v[30:31], v[22:23], v[154:155], v[30:31]
	v_pk_fma_f32 v[28:29], v[20:21], v[152:153], v[28:29]
	s_and_b64 vcc, exec, s[6:7]
	v_pk_fma_f32 v[26:27], v[18:19], v[184:185], v[26:27]
	s_cbranch_vccnz .LBB0_574
	v_cvt_pk_f16_f32 v18, v30, v31
	v_cvt_pk_f16_f32 v19, v32, v33
	v_cvt_pk_f16_f32 v20, v26, v27
	v_cvt_pk_f16_f32 v21, v28, v29
	global_store_dwordx4 v[74:75], v[18:21], off
.LBB0_574:
	s_nop 1
	v_lshl_add_u64 v[18:19], v[180:181], 0, v[82:83]
	s_mov_b64 s[4:5], -1
	s_and_b64 vcc, exec, s[8:9]
	v_lshl_add_u64 v[156:157], v[18:19], 1, s[0:1]
	s_cbranch_vccnz .LBB0_576
	s_mov_b64 s[4:5], 0
	v_cvt_f32_f16_e32 v22, v192
	v_cvt_f32_f16_sdwa v23, v192 dst_sel:DWORD dst_unused:UNUSED_PAD src0_sel:WORD_1
	v_cvt_f32_f16_e32 v24, v193
	v_cvt_f32_f16_sdwa v25, v193 dst_sel:DWORD dst_unused:UNUSED_PAD src0_sel:WORD_1
	v_cvt_f32_f16_e32 v18, v194
	v_cvt_f32_f16_sdwa v19, v194 dst_sel:DWORD dst_unused:UNUSED_PAD src0_sel:WORD_1
	v_cvt_f32_f16_e32 v20, v195
	v_cvt_f32_f16_sdwa v21, v195 dst_sel:DWORD dst_unused:UNUSED_PAD src0_sel:WORD_1
.LBB0_576:
	s_andn2_b64 vcc, exec, s[4:5]
	s_cbranch_vccnz .LBB0_578
	global_load_dwordx4 v[18:21], v[172:173], off offset:528
	global_load_dwordx4 v[22:25], v[172:173], off offset:512
	s_waitcnt vmcnt(0)
.LBB0_578:
	v_pk_fma_f32 v[74:75], v[16:17], v[150:151], v[24:25]
	v_pk_fma_f32 v[78:79], v[14:15], v[154:155], v[22:23]
	v_pk_fma_f32 v[76:77], v[12:13], v[152:153], v[20:21]
	s_and_b64 vcc, exec, s[6:7]
	v_pk_fma_f32 v[80:81], v[10:11], v[184:185], v[18:19]
	s_cbranch_vccnz .LBB0_580
	v_cvt_pk_f16_f32 v10, v78, v79
	v_cvt_pk_f16_f32 v11, v74, v75
	v_cvt_pk_f16_f32 v12, v80, v81
	v_cvt_pk_f16_f32 v13, v76, v77
	global_store_dwordx4 v[156:157], v[10:13], off
.LBB0_580:
	s_nop 1
	v_lshl_add_u64 v[10:11], v[182:183], 0, v[82:83]
	s_mov_b64 s[4:5], -1
	s_and_b64 vcc, exec, s[8:9]
	v_lshl_add_u64 v[18:19], v[10:11], 1, s[0:1]
	s_cbranch_vccnz .LBB0_582
	s_mov_b64 s[4:5], 0
	v_cvt_f32_f16_e32 v14, v198
	v_cvt_f32_f16_sdwa v15, v198 dst_sel:DWORD dst_unused:UNUSED_PAD src0_sel:WORD_1
	v_cvt_f32_f16_e32 v16, v199
	v_cvt_f32_f16_sdwa v17, v199 dst_sel:DWORD dst_unused:UNUSED_PAD src0_sel:WORD_1
	v_cvt_f32_f16_e32 v10, v200
	v_cvt_f32_f16_sdwa v11, v200 dst_sel:DWORD dst_unused:UNUSED_PAD src0_sel:WORD_1
	v_cvt_f32_f16_e32 v12, v201
	v_cvt_f32_f16_sdwa v13, v201 dst_sel:DWORD dst_unused:UNUSED_PAD src0_sel:WORD_1
.LBB0_582:
	s_andn2_b64 vcc, exec, s[4:5]
	s_cbranch_vccnz .LBB0_584
	global_load_dwordx4 v[10:13], v[176:177], off offset:528
	global_load_dwordx4 v[14:17], v[176:177], off offset:512
	s_waitcnt vmcnt(0)
.LBB0_584:
	v_pk_fma_f32 v[150:151], v[8:9], v[150:151], v[16:17]
	v_pk_fma_f32 v[154:155], v[6:7], v[154:155], v[14:15]
	v_pk_fma_f32 v[152:153], v[4:5], v[152:153], v[12:13]
	s_and_b64 vcc, exec, s[6:7]
	v_pk_fma_f32 v[156:157], v[2:3], v[184:185], v[10:11]
	s_cbranch_vccnz .LBB0_586
	v_cvt_pk_f16_f32 v2, v154, v155
	v_cvt_pk_f16_f32 v3, v150, v151
	v_cvt_pk_f16_f32 v4, v156, v157
	v_cvt_pk_f16_f32 v5, v152, v153
	global_store_dwordx4 v[18:19], v[2:5], off
